# attention phases: one static s_setprio 1 for waves 4-7 at phase entry (reset at phase exit), no per-segment flips
# speedup vs baseline: 1.0035x; 1.0019x over previous
.LBB0_703:
	s_or_b64 exec, exec, s[0:1]
	v_mov_b32_e32 v54, v1
	s_waitcnt lgkmcnt(0)
	s_barrier
	s_andn2_b64 vcc, exec, s[96:97]
	v_readfirstlane_b32 s8, v54
	s_barrier
	s_lshr_b32 s99, s8, 6
	s_cmp_lt_u32 s99, 4
	s_cbranch_scc1 .Lprio_ph0
	s_setprio 1
.Lprio_ph0:
	s_cbranch_vccnz .LBB0_729
	v_lshlrev_b32_e32 v2, 4, v54
	v_readlane_b32 s10, v241, 50
	v_and_b32_e32 v107, 0xffffff00, v2
	v_readlane_b32 s11, v241, 51
	v_and_b32_e32 v106, 0xf0, v2
	v_readlane_b32 s0, v241, 48
	v_add_u32_e32 v108, 0xffff8000, v107
	v_cndmask_b32_e64 v2, 0, 1, s[10:11]
	s_waitcnt vmcnt(17)
	v_or_b32_e32 v46, s0, v106
	v_add_u32_e32 v47, s93, v108
	v_cmp_ne_u32_e64 s[0:1], 1, v2
	s_andn2_b64 vcc, exec, s[10:11]
	s_cbranch_vccnz .LBB0_709
	v_lshl_add_u32 v2, v47, s83, v46
	global_load_dwordx4 v[6:9], v2, s[70:71]
	s_and_b64 vcc, exec, s[0:1]
	s_cbranch_vccnz .LBB0_710

.LBB0_729:
	s_setprio 0
	s_waitcnt lgkmcnt(0)
	s_barrier
	s_waitcnt vmcnt(0)
	s_barrier
	s_and_saveexec_b64 s[0:1], s[86:87]
	s_cbranch_execz .LBB0_781
	v_readlane_b32 s8, v241, 26
	s_waitcnt vmcnt(0) expcnt(0) lgkmcnt(0)
	s_nop 0
	v_mov_b32_e32 v2, s8
	ds_read_b32 v5, v2
	v_readlane_b32 s8, v241, 28
	s_waitcnt lgkmcnt(0)
	v_cmp_ne_u32_e32 vcc, 0, v5
	v_mov_b32_e32 v2, s8
	ds_read_b32 v4, v2
	s_cbranch_vccnz .LBB0_745
	s_mov_b32 s14, 1
	s_branch .LBB0_733

.LBB0_781:
	s_or_b64 exec, exec, s[0:1]
	v_readlane_b32 s0, v241, 52
	v_mov_b32_e32 v54, v1
	v_readlane_b32 s1, v241, 53
	s_waitcnt lgkmcnt(0)
	s_barrier
	s_andn2_b64 vcc, exec, s[0:1]
	v_readfirstlane_b32 s8, v54
	s_barrier
	s_lshr_b32 s99, s8, 6
	s_cmp_lt_u32 s99, 4
	s_cbranch_scc1 .Lprio_ph1
	s_setprio 1
.Lprio_ph1:
	s_cbranch_vccnz .LBB0_802
	v_lshlrev_b32_e32 v2, 4, v54
	v_and_b32_e32 v178, 0xf0, v2
	v_readlane_b32 s0, v241, 56
	v_and_b32_e32 v179, 0xffffff00, v2
	v_readlane_b32 s10, v241, 59
	s_waitcnt vmcnt(19)
	v_or_b32_e32 v38, s0, v178
	v_add_u32_e32 v180, 0xffff8000, v179
	v_readlane_b32 s0, v241, 57
	v_readlane_b32 s11, v241, 60
	s_andn2_b64 vcc, exec, s[10:11]
	v_add_u32_e32 v39, s0, v180
	v_cndmask_b32_e64 v2, 0, 1, s[10:11]
	s_waitcnt vmcnt(17)
	v_add_u32_e32 v46, v39, v38
	v_cmp_ne_u32_e64 s[0:1], 1, v2
	s_cbranch_vccnz .LBB0_787
	global_load_dwordx4 v[6:9], v46, s[70:71]
	s_and_b64 vcc, exec, s[0:1]
	s_cbranch_vccnz .LBB0_788
